# t1 + up-projection tile rebalance: scan workgroups take 0 q + 2 kv tiles, workgroups 128..159 take 3 q + 2 kv
# baseline (speedup 1.0000x reference)
.LBB0_384:
	s_mov_b32 s101, s92
	s_cmp_eq_u32 s100, 0
	s_cbranch_scc1 .Lq_noswap
	s_xor_b32 s76, s76, 0x80
	s_cmpk_lt_u32 s76, 32
	s_cselect_b32 s101, 0x80, s92
	s_sub_i32 s0, s76, 0x80
	s_cmpk_lt_u32 s0, 32
	s_cbranch_scc0 .Lq_noswap
	s_or_b32 s76, s76, 0x200

.LBB0_392:
	s_add_i32 s56, s56, 1
	s_mul_i32 s2, s56, s38
	s_mul_hi_u32 s4, s56, s101
	s_add_i32 s4, s4, s2
	s_mul_i32 s2, s56, s101
	s_add_u32 s6, s2, s76
	s_addc_u32 s7, s4, s33
	v_cmp_gt_i64_e32 vcc, s[6:7], v[148:149]
	v_cmp_lt_i64_e64 s[4:5], s[6:7], v[146:147]
	s_cbranch_vccnz .LBB0_394
	s_ashr_i32 s2, s6, 31
	s_lshr_b32 s2, s2, 29
	s_add_i32 s2, s6, s2
	s_ashr_i32 s7, s2, 3
	s_and_b32 s2, s2, -8
	s_sub_i32 s2, s6, s2
	s_cmp_lt_i32 s2, 0
	s_cselect_b32 s6, 49, 48
	s_mul_i32 s2, s2, s6
	s_add_i32 s2, s2, s7
	s_mul_hi_i32 s6, s2, 0x2aaaaaab
	s_lshr_b32 s7, s6, 31
	s_ashr_i32 s6, s6, 3
	s_add_i32 s6, s6, s7
	s_lshl_b32 s7, s6, 3
	s_sub_i32 s28, 64, s7
	s_min_i32 s28, s28, 8
	s_abs_i32 s29, s28
	v_cvt_f32_u32_e32 v0, s29
	s_sub_i32 s35, 0, s29
	s_mul_i32 s6, s6, 48
	s_sub_i32 s2, s2, s6
	v_rcp_iflag_f32_e32 v0, v0
	s_abs_i32 s6, s2
	s_xor_b32 s34, s2, s28
	s_ashr_i32 s34, s34, 31
	v_mul_f32_e32 v0, 0x4f7ffffe, v0
	v_cvt_u32_f32_e32 v0, v0
	s_nop 0
	v_readfirstlane_b32 s57, v0
	s_mul_i32 s35, s35, s57
	s_mul_hi_u32 s35, s57, s35
	s_add_i32 s57, s57, s35
	s_mul_hi_u32 s35, s6, s57
	s_mul_i32 s57, s35, s29
	s_sub_i32 s6, s6, s57
	s_add_i32 s58, s35, 1
	s_sub_i32 s57, s6, s29
	s_cmp_ge_u32 s6, s29
	s_cselect_b32 s35, s58, s35
	s_cselect_b32 s6, s57, s6
	s_add_i32 s57, s35, 1
	s_cmp_ge_u32 s6, s29
	s_cselect_b32 s6, s57, s35
	s_xor_b32 s6, s6, s34
	s_sub_i32 s57, s6, s34
	s_mul_i32 s6, s57, s28
	s_sub_i32 s2, s2, s6
	s_add_i32 s58, s7, s2

.LBB0_438:
	s_mov_b32 s101, s92
	s_cmp_eq_u32 s100, 0
	s_cbranch_scc1 .Lkv_noswap
	s_xor_b32 s76, s76, 0x80
	s_and_b32 s76, s76, 0xff
	s_lshr_b32 s39, s76, 3
	s_movk_i32 s101, 0x200
	s_cmpk_lt_i32 s76, 0x80
	s_cselect_b32 s101, s101, 0x80
	s_cmpk_lt_i32 s76, 32
	s_cselect_b32 s101, 0x180, s101

.LBB0_441:
	s_lshl_b32 s7, s8, 5
	s_mov_b64 s[8:9], 0x80
	s_add_i32 m0, s37, 0x18000
	v_lshl_add_u64 v[6:7], v[6:7], 0, s[8:9]
	s_lshl_b32 s20, s5, 13
	s_and_b32 s21, s7, 0x60
	s_waitcnt vmcnt(2)
	s_barrier
	global_load_lds_dwordx4 v[6:7], off
	v_lshl_add_u64 v[4:5], v[4:5], 0, s[8:9]
	s_add_i32 m0, s37, 0x1a000
	s_add_i32 s42, s37, 0x8000
	s_add_i32 s43, s37, 0xa000
	global_load_lds_dwordx4 v[4:5], off
	v_lshl_add_u64 v[0:1], v[0:1], 0, s[8:9]
	s_mov_b32 m0, s42
	s_add_u32 s14, s30, 0x20080
	global_load_lds_dwordx4 v[0:1], off
	v_lshl_add_u64 v[0:1], v[2:3], 0, s[8:9]
	s_mov_b32 m0, s43
	s_addc_u32 s15, s31, 0
	global_load_lds_dwordx4 v[0:1], off
	s_add_i32 m0, s37, 0x1c000
	v_lshl_add_u64 v[0:1], s[14:15], 0, v[132:133]
	global_load_lds_dwordx4 v[0:1], off
	v_lshl_add_u64 v[0:1], s[14:15], 0, v[136:137]
	s_add_i32 m0, s37, 0x1e000
	v_lshlrev_b32_e32 v2, 10, v156
	global_load_lds_dwordx4 v[0:1], off
	v_lshlrev_b32_e32 v1, 2, v155
	v_lshl_or_b32 v0, v155, 6, v128
	v_and_b32_e32 v1, 32, v1
	v_bitop3_b32 v0, v0, s20, v1 bitop3:0xde
	v_lshlrev_b32_e32 v1, 7, v161
	v_and_b32_e32 v1, 0x1c000, v1
	v_or3_b32 v1, v153, v1, v2
	v_add_u32_e32 v138, v1, v154
	v_lshlrev_b32_e32 v1, 3, v158
	s_waitcnt vmcnt(6)
	s_cmpk_lt_u32 s4, 0x100
	v_and_b32_e32 v1, 0x3c000, v1
	v_lshl_or_b32 v151, s21, 7, v157
	s_cselect_b64 s[14:15], -1, 0
	v_or3_b32 v1, v153, v1, v2
	s_add_i32 s44, 0, 0x10000
	s_add_i32 s45, 0, 0x14000
	s_sext_i32_i8 s7, s0
	v_lshl_or_b32 v150, s5, 6, v155
	v_mov_b32_e32 v139, v129
	v_add_u32_e32 v140, v1, v154
	v_mov_b32_e32 v141, v129
	v_mov_b64_e32 v[142:143], 0x200
	v_mov_b64_e32 v[144:145], 0x1ff
	s_cmp_eq_u32 s100, 0
	s_cbranch_scc1 .Lkv_bound_done
	s_sub_i32 s23, s76, 0x80
	s_cmpk_lt_u32 s23, 32
	s_cbranch_scc0 .Lkv_bound_done
	v_mov_b32_e32 v142, 0x180
	v_mov_b32_e32 v144, 0x17f
.Lkv_bound_done:
	v_add_u32_e32 v152, s44, v151
	v_add_u32_e32 v153, s45, v151
	v_add_u32_e32 v154, 0, v0
	v_mov_b32_e32 v155, 0x358637bd
	s_mov_b32 s46, 0xf800000
	v_mov_b32_e32 v156, 0x260
	s_movk_i32 s47, 0xc00
	s_lshl_b32 s0, s21, 1
	s_mov_b32 s48, s1
	s_barrier
	s_branch .LBB0_444
